# MLA fast path: V rows un-permuted and the 32 P-operand permlane32 swaps removed; nope-K LDS swizzle over row&15 (conflict-free b128 reads)
# speedup vs baseline: 1.1124x; 1.0083x over previous
.LBB0_805:
	s_lshl_b32 s4, s93, 10
	v_mov_b32 v16, v144
	s_and_b32 s5, s4, 0x2000
	v_readfirstlane_b32 s0, v16
	s_lshl_b32 s4, s91, 8
	s_ashr_i32 s1, s0, 6
	s_and_b32 s4, s4, 0x1f00
	s_or_b32 s4, s5, s4
	s_lshl_b32 s6, s1, 5
	v_and_b32_e32 v162, 31, v16
	s_add_i32 s4, s6, s4
	v_or_b32_e32 v2, s4, v162
	v_mov_b64_e32 v[0:1], s[10:11]
	v_mad_i64_i32 v[0:1], s[6:7], v2, s40, v[0:1]
	s_lshl_b32 s6, s5, 12
	s_add_u32 s6, s34, s6
	s_addc_u32 s7, s35, 0
	s_mulk_i32 s5, 0xe00
	v_bfe_u32 v163, v16, 5, 1
	s_add_u32 s14, s28, s5
	v_lshlrev_b32_e32 v148, 4, v163
	v_mov_b32_e32 v149, v147
	s_addc_u32 s15, s29, 0
	s_lshl_b32 s19, s1, 2
	v_bfe_u32 v17, v16, 4, 2
	v_lshl_add_u64 v[24:25], v[0:1], 0, v[148:149]
	v_or_b32_e32 v0, s19, v17
	v_and_b32_e32 v1, 15, v16
	s_ashr_i32 s5, s0, 4
	v_bitop3_b32 v2, v0, v1, 15 bitop3:0x6c
	s_and_b32 s20, s5, -16
	v_bfe_u32 v18, v16, 2, 2
	v_lshrrev_b32_e32 v22, 1, v16
	s_lshr_b32 s5, s5, 1
	v_lshlrev_b32_e32 v146, 4, v2
	v_or_b32_e32 v2, s20, v18
	v_lshrrev_b32_e32 v19, 2, v16
	v_and_b32_e32 v19, 4, v19
	s_and_b32 s21, s5, 4
	s_lshl_b32 s21, s21, 1
	v_or3_b32 v2, v2, v19, s21
	v_ashrrev_i32_e32 v1, 31, v0
	v_ashrrev_i32_e32 v3, 31, v2
	s_lshl_b32 s36, s1, 3
	v_bfe_u32 v20, v16, 3, 3
	v_lshlrev_b64 v[0:1], 12, v[0:1]
	v_lshlrev_b64 v[2:3], 12, v[2:3]
	s_lshl_b32 s5, s1, 1
	v_or_b32_e32 v8, s36, v20
	v_mov_b64_e32 v[6:7], s[14:15]
	s_lshl_b32 s1, s1, 10
	v_lshl_add_u64 v[0:1], s[6:7], 0, v[0:1]
	v_lshl_add_u64 v[2:3], s[6:7], 0, v[2:3]
	v_and_or_b32 v4, s5, 2, v163
	v_mad_i64_i32 v[6:7], s[6:7], v8, s89, v[6:7]
	s_add_i32 s5, s1, 0
	v_lshlrev_b32_e32 v4, 6, v4
	v_mov_b32_e32 v5, v147
	v_lshlrev_b32_e32 v23, 4, v16
	v_lshrrev_b32_e32 v8, 1, v8
	s_add_i32 s6, s5, 0xc000
	v_lshl_add_u64 v[0:1], v[0:1], 0, v[146:147]
	v_lshl_add_u64 v[2:3], v[2:3], 0, v[4:5]
	v_and_b32_e32 v4, 48, v23
	v_xor_b32_e32 v21, v8, v16
	s_mov_b32 m0, s6
	s_add_i32 s7, s5, 0xe000
	s_barrier
	v_lshl_add_u64 v[2:3], v[2:3], 0, v[4:5]
	v_lshlrev_b32_e32 v8, 4, v21
	global_load_lds_dwordx4 v[0:1], off
	v_lshl_add_u64 v[10:11], v[0:1], 0, s[22:23]
	s_mov_b32 m0, s7
	v_lshl_add_u64 v[4:5], v[2:3], 0, s[42:43]
	v_and_b32_e32 v8, 0x70, v8
	v_mov_b32_e32 v9, v147
	global_load_lds_dwordx4 v[10:11], off
	s_mov_b32 m0, s5
	v_lshl_add_u64 v[6:7], v[6:7], 0, v[8:9]
	global_load_lds_dwordx4 v[4:5], off
	v_lshl_add_u64 v[4:5], v[2:3], 0, s[52:53]
	s_add_i32 m0, s5, 0x2000
	v_lshl_add_u64 v[8:9], v[6:7], 0, s[44:45]
	global_load_lds_dwordx4 v[4:5], off
	s_add_i32 m0, s5, 0x14000
	v_lshl_add_u64 v[4:5], v[0:1], 0, s[54:55]
	global_load_lds_dwordx4 v[8:9], off
	s_add_i32 m0, s5, 0x10000
	v_lshl_add_u64 v[0:1], v[0:1], 0, s[56:57]
	global_load_lds_dwordx4 v[4:5], off
	s_add_i32 m0, s5, 0x12000
	v_add_u32_e32 v23, 0, v23
	global_load_lds_dwordx4 v[0:1], off
	v_lshl_add_u64 v[0:1], v[2:3], 0, s[58:59]
	s_add_i32 m0, s5, 0x4000
	v_add_u32_e32 v167, 0x18800, v23
	global_load_lds_dwordx4 v[0:1], off
	v_lshl_add_u64 v[0:1], v[2:3], 0, s[60:61]
	s_add_i32 m0, s5, 0x6000
	s_nop 0
	global_load_lds_dwordx4 v[0:1], off
	v_lshl_add_u64 v[0:1], v[6:7], 0, s[62:63]
	s_add_i32 m0, s5, 0x16000
	s_cmpk_lt_i32 s0, 0x100
	global_load_lds_dwordx4 v[0:1], off
	global_load_dwordx4 v[140:143], v[24:25], off
	global_load_dwordx4 v[136:139], v[24:25], off offset:32
	global_load_dwordx4 v[132:135], v[24:25], off offset:64
	global_load_dwordx4 v[128:131], v[24:25], off offset:96
	global_load_dwordx4 v[124:127], v[24:25], off offset:128
	global_load_dwordx4 v[120:123], v[24:25], off offset:160
	global_load_dwordx4 v[0:3], v[24:25], off offset:256
	global_load_dwordx4 v[4:7], v[24:25], off offset:288
	global_load_dwordx4 v[8:11], v[24:25], off offset:320
	global_load_dwordx4 v[12:15], v[24:25], off offset:352
	global_load_dwordx4 v[116:119], v[24:25], off offset:192
	global_load_dwordx4 v[112:115], v[24:25], off offset:224
	s_waitcnt vmcnt(0)
	ds_write_b128 v167, v[0:3]
	ds_write_b128 v167, v[4:7] offset:8192
	ds_write_b128 v167, v[8:11] offset:16384
	ds_write_b128 v167, v[12:15] offset:24576
	s_cbranch_scc1 .LBB0_807
	s_setprio 1
.LBB0_807:
	v_lshlrev_b32_e32 v0, 4, v162
	v_lshlrev_b32_e32 v23, 8, v162
	v_and_b32_e32 v52, 0xf0, v0
	v_bitop3_b32 v168, v148, v23, v52 bitop3:0xde
	s_waitcnt vmcnt(0)
	v_add_u32_e32 v169, 0, v168
	s_waitcnt lgkmcnt(0)
	s_barrier
	ds_read_b128 v[0:3], v169 offset:49152
	ds_read_b128 v[24:27], v169 offset:57344
	v_or_b32_e32 v28, 32, v148
	v_bitop3_b32 v170, v28, v23, v52 bitop3:0xde
	v_add_u32_e32 v171, 0, v170
	s_waitcnt lgkmcnt(0)
	v_mfma_f32_32x32x16_bf16 v[64:79], v[24:27], v[140:143], 0
	ds_read_b128 v[24:27], v171 offset:49152
	v_or_b32_e32 v28, 64, v148
	v_bitop3_b32 v172, v28, v23, v52 bitop3:0xde
	v_add_u32_e32 v173, 0, v172
	ds_read_b128 v[28:31], v171 offset:57344
	v_or_b32_e32 v32, 0x60, v148
	v_bitop3_b32 v174, v32, v23, v52 bitop3:0xde
	v_mfma_f32_32x32x16_bf16 v[0:15], v[0:3], v[140:143], 0
	v_add_u32_e32 v175, 0, v174
	ds_read_b128 v[32:35], v173 offset:57344
	v_or_b32_e32 v36, 0x80, v148
	v_bitop3_b32 v176, v36, v23, v52 bitop3:0xde
	v_add_u32_e32 v177, 0, v176
	v_or_b32_e32 v53, 0xe0, v148
	v_bitop3_b32 v182, v53, v23, v52 bitop3:0xde
	s_waitcnt lgkmcnt(2)
	v_mfma_f32_32x32x16_bf16 v[0:15], v[24:27], v[136:139], v[0:15]
	ds_read_b128 v[24:27], v173 offset:49152
	v_add_u32_e32 v183, 0, v182
	s_cmp_lg_u32 0, -1
	v_lshlrev_b32_e32 v96, 7, v162
	v_bitop3_b32 v22, v163, v22, 7 bitop3:0x78
	s_cselect_b32 s37, 0, 0
	v_lshl_or_b32 v184, v22, 4, v96
	s_waitcnt lgkmcnt(0)
	v_mfma_f32_32x32x16_bf16 v[0:15], v[24:27], v[132:135], v[0:15]
	ds_read_b128 v[24:27], v175 offset:49152
	ds_read_b128 v[36:39], v175 offset:57344
	ds_read_b128 v[40:43], v177 offset:49152
	s_add_i32 s14, 0, 0x14000
	v_bfe_u32 v97, v16, 1, 3
	v_add_u32_e32 v185, s14, v184
	v_bitop3_b32 v22, v163, v97, 2 bitop3:0x36
	v_lshl_or_b32 v186, v22, 4, v96
	v_mfma_f32_32x32x16_bf16 v[64:79], v[28:31], v[136:139], v[64:79]
	v_add_u32_e32 v187, s14, v186
	v_and_b32_e32 v149, 63, v16
	v_lshlrev_b32_e32 v98, 4, v149
	v_and_b32_e32 v105, 0xc0, v98
	v_lshlrev_b32_e32 v104, 3, v149
	v_lshlrev_b32_e32 v22, 1, v149
	v_and_b32_e32 v22, 32, v22
	s_waitcnt lgkmcnt(2)
	v_mfma_f32_32x32x16_bf16 v[0:15], v[24:27], v[128:131], v[0:15]
	v_or_b32_e32 v24, 0xa0, v148
	v_bitop3_b32 v178, v24, v23, v52 bitop3:0xde
	v_add_u32_e32 v179, 0, v178
	ds_read_b128 v[24:27], v177 offset:57344
	ds_read_b128 v[44:47], v179 offset:49152
	s_mov_b32 s15, -1
	s_mov_b32 s18, 0
	v_mfma_f32_32x32x16_bf16 v[64:79], v[32:35], v[132:135], v[64:79]
	v_mov_b32_e32 v32, 0
	s_waitcnt lgkmcnt(2)
	v_mfma_f32_32x32x16_bf16 v[0:15], v[40:43], v[124:127], v[0:15]
	v_or_b32_e32 v40, 0xc0, v148
	v_bitop3_b32 v180, v40, v23, v52 bitop3:0xde
	v_add_u32_e32 v181, 0, v180
	ds_read_b128 v[40:43], v179 offset:57344
	ds_read_b128 v[48:51], v181 offset:49152
	v_bitop3_b32 v23, v163, v97, 4 bitop3:0x36
	v_lshl_or_b32 v188, v23, 4, v96
	v_add_u32_e32 v189, s14, v188
	v_mfma_f32_32x32x16_bf16 v[64:79], v[36:39], v[128:131], v[64:79]
	v_bitop3_b32 v23, v163, v97, 6 bitop3:0x36
	v_lshl_or_b32 v190, v23, 4, v96
	v_add_u32_e32 v191, s14, v190
	v_and_b32_e32 v23, 0x100, v104
	s_waitcnt lgkmcnt(2)
	v_mfma_f32_32x32x16_bf16 v[0:15], v[44:47], v[120:123], v[0:15]
	ds_read_b128 v[44:47], v181 offset:57344
	ds_read_b128 v[52:55], v183 offset:49152
	v_mfma_f32_32x32x16_bf16 v[64:79], v[24:27], v[124:127], v[64:79]
	s_waitcnt lgkmcnt(2)
	v_mfma_f32_32x32x16_bf16 v[0:15], v[48:51], v[116:119], v[0:15]
	ds_read_b128 v[48:51], v185
	ds_read_b128 v[56:59], v183 offset:57344
	v_mfma_f32_32x32x16_bf16 v[64:79], v[40:43], v[120:123], v[64:79]
	s_waitcnt lgkmcnt(2)
	v_mfma_f32_32x32x16_bf16 v[0:15], v[52:55], v[112:115], v[0:15]
	ds_read_b128 v[52:55], v167
	ds_read_b128 v[60:63], v167 offset:8192
	ds_read_b128 v[80:83], v185 offset:4096
	ds_read_b128 v[84:87], v187
	v_mfma_f32_32x32x16_bf16 v[64:79], v[44:47], v[116:119], v[64:79]
	s_waitcnt lgkmcnt(3)
	v_mfma_f32_32x32x16_bf16 v[0:15], v[48:51], v[52:55], v[0:15]
	ds_read_b128 v[48:51], v187 offset:4096
	ds_read_b128 v[88:91], v189
	v_mfma_f32_32x32x16_bf16 v[64:79], v[56:59], v[112:115], v[64:79]
	s_waitcnt lgkmcnt(2)
	v_mfma_f32_32x32x16_bf16 v[0:15], v[84:87], v[60:63], v[0:15]
	ds_read_b128 v[84:87], v167 offset:16384
	ds_read_b128 v[92:95], v167 offset:24576
	ds_read_b128 v[96:99], v189 offset:4096
	ds_read_b128 v[100:103], v191
	v_mfma_f32_32x32x16_bf16 v[64:79], v[80:83], v[52:55], v[64:79]
	s_waitcnt lgkmcnt(3)
	v_mfma_f32_32x32x16_bf16 v[0:15], v[88:91], v[84:87], v[0:15]
	v_and_or_b32 v88, v104, 24, v105
	v_or3_b32 v165, v88, v22, v23
	ds_read_b128 v[88:91], v191 offset:4096
	v_add_u32_e32 v166, s37, v165
	v_mfma_f32_32x32x16_bf16 v[64:79], v[48:51], v[60:63], v[64:79]
	v_mov_b32_e32 v48, 0
	s_waitcnt lgkmcnt(1)
	v_mfma_f32_32x32x16_bf16 v[0:15], v[100:103], v[92:95], v[0:15]
	v_mfma_f32_32x32x16_bf16 v[64:79], v[96:99], v[84:87], v[64:79]
	s_nop 10
	v_exp_f32_e32 v211, v0
	v_exp_f32_e32 v213, v1
	v_exp_f32_e32 v209, v2
	v_add_u32_e32 v2, s36, v20
	v_mov_b64_e32 v[0:1], s[8:9]
	v_mad_i64_i32 v[0:1], s[36:37], v2, s89, v[0:1]
	v_and_b32_e32 v2, 7, v21
	s_add_u32 s36, s27, s92
	v_exp_f32_e32 v212, v3
	v_lshlrev_b32_e32 v2, 4, v2
	v_mov_b32_e32 v3, v147
	s_addc_u32 s37, 0, 0
	s_add_i32 s21, s21, s20
	v_lshl_add_u64 v[150:151], v[0:1], 0, v[2:3]
	v_add3_u32 v0, s21, v19, v18
	v_ashrrev_i32_e32 v1, 31, v0
	v_lshlrev_b64 v[0:1], 12, v[0:1]
	v_and_b32_e32 v2, 3, v16
	s_lshl_b32 s8, s0, 1
	v_lshl_add_u64 v[0:1], s[36:37], 0, v[0:1]
	v_lshlrev_b32_e32 v2, 4, v2
	s_and_b32 s8, s8, 0x80
	s_waitcnt lgkmcnt(0)
	v_mfma_f32_32x32x16_bf16 v[64:79], v[88:91], v[92:95], v[64:79]
	v_lshl_add_u64 v[0:1], v[0:1], 0, v[2:3]
	v_lshl_or_b32 v2, v163, 6, s8
	v_lshl_add_u64 v[152:153], v[0:1], 0, v[2:3]
	v_add_u32_e32 v0, s19, v17
	v_ashrrev_i32_e32 v1, 31, v0
	v_exp_f32_e32 v208, v4
	v_exp_f32_e32 v210, v5
	v_exp_f32_e32 v206, v6
	v_exp_f32_e32 v207, v7
	v_exp_f32_e32 v161, v8
	v_exp_f32_e32 v205, v9
	v_exp_f32_e32 v160, v10
	v_exp_f32_e32 v204, v11
	v_exp_f32_e32 v157, v12
	v_exp_f32_e32 v159, v13
	v_exp_f32_e32 v156, v14
	v_exp_f32_e32 v158, v15
	v_lshlrev_b64 v[0:1], 12, v[0:1]
	v_lshl_add_u64 v[0:1], s[36:37], 0, v[0:1]
	v_lshl_add_u64 v[154:155], v[0:1], 0, v[146:147]
	v_mov_b32_e32 v146, 0
	v_mov_b32_e32 v0, 0
	v_mov_b32_e32 v1, v146
	v_mov_b32_e32 v2, v146
	v_mov_b32_e32 v3, v146
	v_mov_b32_e32 v4, v146
	v_mov_b32_e32 v5, v146
	v_mov_b32_e32 v6, v146
	v_mov_b32_e32 v7, v146
	v_mov_b32_e32 v8, v146
	v_mov_b32_e32 v9, v146
	v_mov_b32_e32 v10, v146
	v_mov_b32_e32 v11, v146
	v_mov_b32_e32 v12, v146
	v_mov_b32_e32 v13, v146
	v_mov_b32_e32 v14, v146
	v_mov_b32_e32 v15, v146
	v_mov_b32_e32 v16, 0
	v_mov_b32_e32 v17, v146
	v_mov_b32_e32 v18, v146
	v_mov_b32_e32 v19, v146
	v_mov_b32_e32 v20, v146
	v_mov_b32_e32 v21, v146
	v_mov_b32_e32 v22, v146
	v_mov_b32_e32 v23, v146
	v_mov_b32_e32 v24, v146
	v_mov_b32_e32 v25, v146
	v_mov_b32_e32 v26, v146
	v_mov_b32_e32 v27, v146
	v_mov_b32_e32 v28, v146
	v_mov_b32_e32 v29, v146
	v_mov_b32_e32 v30, v146
	v_mov_b32_e32 v31, v146
	v_mov_b32_e32 v33, v146
	v_mov_b32_e32 v34, v146
	v_mov_b32_e32 v35, v146
	v_mov_b32_e32 v36, v146
	v_mov_b32_e32 v37, v146
	v_mov_b32_e32 v38, v146
	v_mov_b32_e32 v39, v146
	v_mov_b32_e32 v40, v146
	v_mov_b32_e32 v41, v146
	v_mov_b32_e32 v42, v146
	v_mov_b32_e32 v43, v146
	v_mov_b32_e32 v44, v146
	v_mov_b32_e32 v45, v146
	v_mov_b32_e32 v46, v146
	v_mov_b32_e32 v47, v146
	v_mov_b32_e32 v49, v146
	v_mov_b32_e32 v50, v146
	v_mov_b32_e32 v51, v146
	v_mov_b32_e32 v52, v146
	v_mov_b32_e32 v53, v146
	v_mov_b32_e32 v54, v146
	v_mov_b32_e32 v55, v146
	v_mov_b32_e32 v56, v146
	v_mov_b32_e32 v57, v146
	v_mov_b32_e32 v58, v146
	v_mov_b32_e32 v59, v146
	v_mov_b32_e32 v60, v146
	v_mov_b32_e32 v61, v146
	v_mov_b32_e32 v62, v146
	v_mov_b32_e32 v63, v146
.LBB0_808:
	s_waitcnt vmcnt(0)
	s_waitcnt lgkmcnt(0)
	s_barrier
	s_add_i32 s8, 0, 0x10000
	v_add_u32_e32 v192, s8, v168
	ds_read_b128 v[80:83], v192
	ds_read_b128 v[84:87], v192 offset:8192
	v_add_u32_e32 v193, s8, v170
	ds_read_b128 v[194:197], v193
	ds_read_b128 v[198:201], v193 offset:8192
	s_add_i32 s19, 0, 0x16000
	s_waitcnt lgkmcnt(0)
	v_mfma_f32_32x32x16_bf16 v[96:111], v[80:83], v[140:143], 0
	v_exp_f32_e32 v226, v76
	v_exp_f32_e32 v227, v77
	v_exp_f32_e32 v228, v78
	v_exp_f32_e32 v79, v79
	v_cvt_pk_bf16_f32 v78, v226, v227
	s_waitcnt lgkmcnt(2)
	v_mfma_f32_32x32x16_bf16 v[80:95], v[84:87], v[140:143], 0
	s_waitcnt lgkmcnt(1)
	v_mfma_f32_32x32x16_bf16 v[96:111], v[194:197], v[136:139], v[96:111]
	v_add_u32_e32 v194, s8, v172
	v_add_u32_e32 v195, s8, v174
	s_waitcnt lgkmcnt(0)
	v_mfma_f32_32x32x16_bf16 v[80:95], v[198:201], v[136:139], v[80:95]
	ds_read_b128 v[196:199], v194
	ds_read_b128 v[200:203], v194 offset:8192
	s_waitcnt lgkmcnt(0)
	v_mfma_f32_32x32x16_bf16 v[96:111], v[196:199], v[132:135], v[96:111]
	s_waitcnt lgkmcnt(0)
	v_mfma_f32_32x32x16_bf16 v[80:95], v[200:203], v[132:135], v[80:95]
	ds_read_b128 v[196:199], v195
	ds_read_b128 v[200:203], v195 offset:8192
	s_waitcnt lgkmcnt(0)
	v_mfma_f32_32x32x16_bf16 v[96:111], v[196:199], v[128:131], v[96:111]
	v_add_u32_e32 v196, s8, v176
	v_add_u32_e32 v197, s8, v178
	s_waitcnt lgkmcnt(0)
	v_mfma_f32_32x32x16_bf16 v[80:95], v[200:203], v[128:131], v[80:95]
	ds_read_b128 v[198:201], v196
	ds_read_b128 v[214:217], v196 offset:8192
	s_waitcnt lgkmcnt(0)
	v_mfma_f32_32x32x16_bf16 v[96:111], v[198:201], v[124:127], v[96:111]
	s_waitcnt lgkmcnt(0)
	v_mfma_f32_32x32x16_bf16 v[80:95], v[214:217], v[124:127], v[80:95]
	ds_read_b128 v[198:201], v197
	ds_read_b128 v[214:217], v197 offset:8192
	s_waitcnt lgkmcnt(0)
	v_mfma_f32_32x32x16_bf16 v[96:111], v[198:201], v[120:123], v[96:111]
	v_add_u32_e32 v198, s8, v180
	v_add_u32_e32 v199, s8, v182
	s_waitcnt lgkmcnt(0)
	v_mfma_f32_32x32x16_bf16 v[80:95], v[214:217], v[120:123], v[80:95]
	ds_read_b128 v[200:203], v198
	ds_read_b128 v[214:217], v198 offset:8192
	s_waitcnt lgkmcnt(0)
	v_mfma_f32_32x32x16_bf16 v[96:111], v[200:203], v[116:119], v[96:111]
	s_waitcnt lgkmcnt(0)
	v_mfma_f32_32x32x16_bf16 v[80:95], v[214:217], v[116:119], v[80:95]
	ds_read_b128 v[200:203], v199
	ds_read_b128 v[214:217], v199 offset:8192
	s_waitcnt lgkmcnt(0)
	v_mfma_f32_32x32x16_bf16 v[96:111], v[200:203], v[112:115], v[96:111]
	v_add_u32_e32 v200, s19, v184
	v_add_u32_e32 v201, s19, v186
	v_add_u32_e32 v202, s19, v188
	v_add_u32_e32 v203, s19, v190
	s_waitcnt lgkmcnt(0)
	v_mfma_f32_32x32x16_bf16 v[80:95], v[214:217], v[112:115], v[80:95]
	ds_read_b128 v[214:217], v167
	ds_read_b128 v[218:221], v200
	ds_read_b128 v[222:225], v200 offset:4096
	s_waitcnt lgkmcnt(0)
	v_mfma_f32_32x32x16_bf16 v[96:111], v[218:221], v[214:217], v[96:111]
	s_waitcnt lgkmcnt(0)
	v_mfma_f32_32x32x16_bf16 v[80:95], v[222:225], v[214:217], v[80:95]
	ds_read_b128 v[214:217], v167 offset:8192
	ds_read_b128 v[218:221], v201
	ds_read_b128 v[222:225], v201 offset:4096
	s_waitcnt lgkmcnt(0)
	v_mfma_f32_32x32x16_bf16 v[96:111], v[218:221], v[214:217], v[96:111]
	s_waitcnt lgkmcnt(0)
	v_mfma_f32_32x32x16_bf16 v[80:95], v[222:225], v[214:217], v[80:95]
	ds_read_b128 v[214:217], v167 offset:16384
	ds_read_b128 v[218:221], v202
	ds_read_b128 v[222:225], v202 offset:4096
	s_waitcnt lgkmcnt(0)
	v_mfma_f32_32x32x16_bf16 v[96:111], v[218:221], v[214:217], v[96:111]
	s_waitcnt lgkmcnt(0)
	v_mfma_f32_32x32x16_bf16 v[80:95], v[222:225], v[214:217], v[80:95]
	ds_read_b128 v[214:217], v167 offset:24576
	ds_read_b128 v[218:221], v203
	ds_read_b128 v[222:225], v203 offset:4096
	s_waitcnt lgkmcnt(0)
	v_mfma_f32_32x32x16_bf16 v[96:111], v[218:221], v[214:217], v[96:111]
	v_exp_f32_e32 v218, v68
	v_exp_f32_e32 v219, v69
	v_exp_f32_e32 v220, v70
	v_exp_f32_e32 v221, v71
	v_cvt_pk_bf16_f32 v68, v211, v213
	v_cvt_pk_bf16_f32 v69, v209, v212
	v_cvt_pk_bf16_f32 v70, v208, v210
	s_waitcnt lgkmcnt(0)
	v_mfma_f32_32x32x16_bf16 v[80:95], v[222:225], v[214:217], v[80:95]
	v_exp_f32_e32 v214, v64
	v_add_f32_e32 v64, 0, v211
	v_add_f32_e32 v64, v213, v64
	v_add_f32_e32 v64, v209, v64
	v_add_f32_e32 v64, v212, v64
	v_add_f32_e32 v64, v208, v64
	v_add_f32_e32 v64, v210, v64
	v_add_f32_e32 v64, v206, v64
	v_add_f32_e32 v64, v207, v64
	v_add_f32_e32 v64, v161, v64
	v_add_f32_e32 v64, v205, v64
	v_add_f32_e32 v64, v160, v64
	v_add_f32_e32 v64, v204, v64
	v_add_f32_e32 v64, v157, v64
	v_exp_f32_e32 v215, v65
	v_add_f32_e32 v64, v159, v64
	v_exp_f32_e32 v216, v66
	v_add_f32_e32 v64, v156, v64
	v_exp_f32_e32 v217, v67
	v_add_f32_e32 v64, v158, v64
	v_add_f32_e32 v64, v214, v64
	v_add_f32_e32 v64, v215, v64
	v_add_f32_e32 v64, v216, v64
	v_add_f32_e32 v64, v217, v64
	v_exp_f32_e32 v222, v72
	v_add_f32_e32 v64, v218, v64
	v_exp_f32_e32 v223, v73
	v_add_f32_e32 v64, v219, v64
	v_exp_f32_e32 v224, v74
	v_add_f32_e32 v64, v220, v64
	v_exp_f32_e32 v225, v75
	v_add_f32_e32 v64, v221, v64
	v_add_f32_e32 v64, v222, v64
	v_add_f32_e32 v64, v223, v64
	v_add_f32_e32 v64, v224, v64
	v_add_f32_e32 v64, v225, v64
	v_add_f32_e32 v64, v226, v64
	v_add_f32_e32 v64, v227, v64
	v_add_f32_e32 v64, v228, v64
	v_add_f32_e32 v64, v79, v64
	v_mov_b32_e32 v65, v64
	s_nop 1
	v_permlane32_swap_b32_e32 v64, v65
	v_add_f32_e32 v64, v64, v65
	v_add_f32_e32 v146, v146, v64
	v_cvt_pk_bf16_f32 v71, v206, v207
	v_cvt_pk_bf16_f32 v64, v161, v205
	v_cvt_pk_bf16_f32 v65, v160, v204
	v_cvt_pk_bf16_f32 v66, v157, v159
	v_cvt_pk_bf16_f32 v67, v156, v158
	v_cvt_pk_bf16_f32 v72, v214, v215
	v_cvt_pk_bf16_f32 v73, v216, v217
	v_cvt_pk_bf16_f32 v74, v218, v219
	v_cvt_pk_bf16_f32 v75, v220, v221
	v_cvt_pk_bf16_f32 v76, v222, v223
	v_cvt_pk_bf16_f32 v77, v224, v225
	v_cvt_pk_bf16_f32 v79, v228, v79
	s_cmp_gt_i32 s18, 0
	s_cselect_b32 s20, -1, 2
	v_lshl_add_u64 v[158:159], s[28:29], 0, v[154:155]
	s_mov_b32 m0, s6
	s_add_i32 s20, s20, s18
	v_lshl_add_u64 v[156:157], v[158:159], 0, s[64:65]
	global_load_lds_dwordx4 v[156:157], off
	v_lshl_add_u64 v[156:157], v[158:159], 0, s[66:67]
	s_mov_b32 m0, s7
	s_lshl_b32 s20, s20, 14
	global_load_lds_dwordx4 v[156:157], off
	v_lshl_add_u64 v[156:157], s[28:29], 0, v[152:153]
	s_add_i32 s20, s5, s20
	v_lshl_add_u64 v[160:161], v[156:157], 0, s[68:69]
	s_mov_b32 m0, s20
	s_nop 0
	global_load_lds_dwordx4 v[160:161], off
	v_lshl_add_u64 v[160:161], v[156:157], 0, s[70:71]
	s_add_i32 m0, s20, 0x2000
	s_nop 0
	global_load_lds_dwordx4 v[160:161], off
	v_lshl_add_u64 v[160:161], s[28:29], 0, v[150:151]
	v_lshl_add_u64 v[204:205], v[160:161], 0, s[72:73]
	s_add_i32 m0, s14, s1
	s_nop 0
	global_load_lds_dwordx4 v[204:205], off
	v_lshl_add_u32 v224, s18, 14, v166
	ds_read_b64_tr_b16 v[204:205], v224 offset:0
	ds_read_b64_tr_b16 v[206:207], v224 offset:0x800
	ds_read_b64_tr_b16 v[208:209], v224 offset:0x1000
	ds_read_b64_tr_b16 v[210:211], v224 offset:0x1800
	ds_read_b64_tr_b16 v[212:213], v224 offset:0x2000
	ds_read_b64_tr_b16 v[214:215], v224 offset:0x2800
	ds_read_b64_tr_b16 v[216:217], v224 offset:0x3000
	ds_read_b64_tr_b16 v[218:219], v224 offset:0x3800
	s_add_i32 s20, s18, 1
	s_waitcnt lgkmcnt(0)
	s_cmp_lg_u32 s18, 2
	v_mfma_f32_32x32x16_bf16 v[48:63], v[68:71], v[204:207], v[48:63]
	ds_read_b64_tr_b16 v[204:205], v224 offset:0x200
	ds_read_b64_tr_b16 v[206:207], v224 offset:0xa00
	s_cselect_b32 s18, s20, 0
	v_exp_f32_e32 v225, v101
	v_exp_f32_e32 v226, v102
	v_exp_f32_e32 v227, v103
	v_exp_f32_e32 v228, v104
	v_mfma_f32_32x32x16_bf16 v[48:63], v[64:67], v[208:211], v[48:63]
	ds_read_b64_tr_b16 v[208:209], v224 offset:0x1200
	ds_read_b64_tr_b16 v[210:211], v224 offset:0x1a00
	v_exp_f32_e32 v229, v105
	v_exp_f32_e32 v230, v106
	v_exp_f32_e32 v231, v107
	v_exp_f32_e32 v232, v108
	v_exp_f32_e32 v233, v109
	v_mfma_f32_32x32x16_bf16 v[48:63], v[72:75], v[212:215], v[48:63]
	ds_read_b64_tr_b16 v[212:213], v224 offset:0x2200
	ds_read_b64_tr_b16 v[214:215], v224 offset:0x2a00
	ds_read_b64_tr_b16 v[220:221], v224 offset:0x3200
	ds_read_b64_tr_b16 v[222:223], v224 offset:0x3a00
	v_exp_f32_e32 v234, v110
	s_waitcnt lgkmcnt(0)
	v_exp_f32_e32 v235, v111
	v_mfma_f32_32x32x16_bf16 v[32:47], v[68:71], v[204:207], v[32:47]
	ds_read_b64_tr_b16 v[204:205], v224 offset:0x400
	ds_read_b64_tr_b16 v[206:207], v224 offset:0xc00
	v_mfma_f32_32x32x16_bf16 v[32:47], v[64:67], v[208:211], v[32:47]
	ds_read_b64_tr_b16 v[208:209], v224 offset:0x1400
	ds_read_b64_tr_b16 v[210:211], v224 offset:0x1c00
	v_mfma_f32_32x32x16_bf16 v[48:63], v[76:79], v[216:219], v[48:63]
	v_mfma_f32_32x32x16_bf16 v[32:47], v[72:75], v[212:215], v[32:47]
	ds_read_b64_tr_b16 v[212:213], v224 offset:0x2400
	ds_read_b64_tr_b16 v[214:215], v224 offset:0x2c00
	ds_read_b64_tr_b16 v[216:217], v224 offset:0x3400
	ds_read_b64_tr_b16 v[218:219], v224 offset:0x3c00
	s_nop 0
	s_waitcnt lgkmcnt(0)
	s_nop 0
	v_mfma_f32_32x32x16_bf16 v[16:31], v[68:71], v[204:207], v[16:31]
	ds_read_b64_tr_b16 v[204:205], v224 offset:0x600
	ds_read_b64_tr_b16 v[206:207], v224 offset:0xe00
	v_mfma_f32_32x32x16_bf16 v[16:31], v[64:67], v[208:211], v[16:31]
	ds_read_b64_tr_b16 v[208:209], v224 offset:0x1600
	ds_read_b64_tr_b16 v[210:211], v224 offset:0x1e00
	v_mfma_f32_32x32x16_bf16 v[16:31], v[72:75], v[212:215], v[16:31]
	ds_read_b64_tr_b16 v[212:213], v224 offset:0x2600
	ds_read_b64_tr_b16 v[214:215], v224 offset:0x2e00
	v_mfma_f32_32x32x16_bf16 v[16:31], v[76:79], v[216:219], v[16:31]
	ds_read_b64_tr_b16 v[216:217], v224 offset:0x3600
	ds_read_b64_tr_b16 v[218:219], v224 offset:0x3e00
	v_exp_f32_e32 v224, v100
	s_waitcnt lgkmcnt(0)
	s_waitcnt vmcnt(0)
	s_waitcnt lgkmcnt(0)
	s_barrier
	v_mfma_f32_32x32x16_bf16 v[0:15], v[68:71], v[204:207], v[0:15]
	v_mfma_f32_32x32x16_bf16 v[0:15], v[64:67], v[208:211], v[0:15]
	v_mfma_f32_32x32x16_bf16 v[0:15], v[72:75], v[212:215], v[0:15]
	v_mfma_f32_32x32x16_bf16 v[32:47], v[76:79], v[220:223], v[32:47]
	v_exp_f32_e32 v220, v96
	v_exp_f32_e32 v221, v97
	v_exp_f32_e32 v222, v98
	v_exp_f32_e32 v223, v99
	v_mfma_f32_32x32x16_bf16 v[0:15], v[76:79], v[216:219], v[0:15]
	ds_read_b128 v[64:67], v169 offset:49152
	ds_read_b128 v[68:71], v169 offset:57344
	ds_read_b128 v[204:207], v171 offset:49152
	ds_read_b128 v[208:211], v171 offset:57344
	v_exp_f32_e32 v80, v80
	v_exp_f32_e32 v81, v81
	s_waitcnt lgkmcnt(0)
	v_mfma_f32_32x32x16_bf16 v[96:111], v[64:67], v[140:143], 0
	v_exp_f32_e32 v82, v82
	v_exp_f32_e32 v83, v83
	v_mfma_f32_32x32x16_bf16 v[64:79], v[68:71], v[140:143], 0
	v_mfma_f32_32x32x16_bf16 v[96:111], v[204:207], v[136:139], v[96:111]
	v_mfma_f32_32x32x16_bf16 v[64:79], v[208:211], v[136:139], v[64:79]
	ds_read_b128 v[204:207], v173 offset:49152
	ds_read_b128 v[208:211], v173 offset:57344
	s_waitcnt lgkmcnt(0)
	v_mfma_f32_32x32x16_bf16 v[96:111], v[204:207], v[132:135], v[96:111]
	v_mfma_f32_32x32x16_bf16 v[64:79], v[208:211], v[132:135], v[64:79]
	ds_read_b128 v[204:207], v175 offset:49152
	ds_read_b128 v[208:211], v175 offset:57344
	s_waitcnt lgkmcnt(0)
	v_mfma_f32_32x32x16_bf16 v[96:111], v[204:207], v[128:131], v[96:111]
	v_mfma_f32_32x32x16_bf16 v[64:79], v[208:211], v[128:131], v[64:79]
	ds_read_b128 v[204:207], v177 offset:49152
	ds_read_b128 v[208:211], v177 offset:57344
	s_waitcnt lgkmcnt(0)
	v_mfma_f32_32x32x16_bf16 v[96:111], v[204:207], v[124:127], v[96:111]
	v_mfma_f32_32x32x16_bf16 v[64:79], v[208:211], v[124:127], v[64:79]
	ds_read_b128 v[204:207], v179 offset:49152
	ds_read_b128 v[208:211], v179 offset:57344
	s_waitcnt lgkmcnt(0)
	v_mfma_f32_32x32x16_bf16 v[96:111], v[204:207], v[120:123], v[96:111]
	v_mfma_f32_32x32x16_bf16 v[64:79], v[208:211], v[120:123], v[64:79]
	ds_read_b128 v[204:207], v181 offset:49152
	ds_read_b128 v[208:211], v181 offset:57344
	s_waitcnt lgkmcnt(0)
	v_mfma_f32_32x32x16_bf16 v[96:111], v[204:207], v[116:119], v[96:111]
	v_mfma_f32_32x32x16_bf16 v[64:79], v[208:211], v[116:119], v[64:79]
	ds_read_b128 v[204:207], v183 offset:49152
	ds_read_b128 v[208:211], v183 offset:57344
	s_waitcnt lgkmcnt(0)
	v_mfma_f32_32x32x16_bf16 v[96:111], v[204:207], v[112:115], v[96:111]
	v_mfma_f32_32x32x16_bf16 v[64:79], v[208:211], v[112:115], v[64:79]
	ds_read_b128 v[204:207], v167
	ds_read_b128 v[208:211], v185
	ds_read_b128 v[212:215], v185 offset:4096
	s_waitcnt lgkmcnt(0)
	v_mfma_f32_32x32x16_bf16 v[96:111], v[208:211], v[204:207], v[96:111]
	v_mfma_f32_32x32x16_bf16 v[64:79], v[212:215], v[204:207], v[64:79]
	ds_read_b128 v[204:207], v167 offset:8192
	ds_read_b128 v[208:211], v187
	ds_read_b128 v[212:215], v187 offset:4096
	s_waitcnt lgkmcnt(0)
	v_mfma_f32_32x32x16_bf16 v[96:111], v[208:211], v[204:207], v[96:111]
	v_mfma_f32_32x32x16_bf16 v[64:79], v[212:215], v[204:207], v[64:79]
	ds_read_b128 v[204:207], v167 offset:16384
	ds_read_b128 v[208:211], v189
	ds_read_b128 v[212:215], v189 offset:4096
	s_waitcnt lgkmcnt(0)
	v_mfma_f32_32x32x16_bf16 v[96:111], v[208:211], v[204:207], v[96:111]
	v_mfma_f32_32x32x16_bf16 v[64:79], v[212:215], v[204:207], v[64:79]
	ds_read_b128 v[204:207], v167 offset:24576
	ds_read_b128 v[208:211], v191
	ds_read_b128 v[212:215], v191 offset:4096
	s_waitcnt lgkmcnt(0)
	v_mfma_f32_32x32x16_bf16 v[96:111], v[208:211], v[204:207], v[96:111]
	v_exp_f32_e32 v208, v88
	v_exp_f32_e32 v209, v89
	v_exp_f32_e32 v210, v90
	v_exp_f32_e32 v211, v91
	v_cvt_pk_bf16_f32 v88, v228, v229
	v_cvt_pk_bf16_f32 v89, v230, v231
	v_cvt_pk_bf16_f32 v90, v232, v233
	v_mfma_f32_32x32x16_bf16 v[64:79], v[212:215], v[204:207], v[64:79]
	v_exp_f32_e32 v204, v84
	v_add_f32_e32 v84, 0, v220
	v_add_f32_e32 v84, v221, v84
	v_add_f32_e32 v84, v222, v84
	v_add_f32_e32 v84, v223, v84
	v_add_f32_e32 v84, v224, v84
	v_add_f32_e32 v84, v225, v84
	v_add_f32_e32 v84, v226, v84
	v_add_f32_e32 v84, v227, v84
	v_add_f32_e32 v84, v228, v84
	v_add_f32_e32 v84, v229, v84
	v_add_f32_e32 v84, v230, v84
	v_add_f32_e32 v84, v231, v84
	v_add_f32_e32 v84, v232, v84
	v_add_f32_e32 v84, v233, v84
	v_add_f32_e32 v84, v234, v84
	v_add_f32_e32 v84, v235, v84
	v_add_f32_e32 v84, v80, v84
	v_exp_f32_e32 v205, v85
	v_add_f32_e32 v84, v81, v84
	v_exp_f32_e32 v206, v86
	v_add_f32_e32 v84, v82, v84
	v_exp_f32_e32 v207, v87
	v_add_f32_e32 v84, v83, v84
	v_add_f32_e32 v84, v204, v84
	v_add_f32_e32 v84, v205, v84
	v_add_f32_e32 v84, v206, v84
	v_add_f32_e32 v84, v207, v84
	v_exp_f32_e32 v212, v92
	v_add_f32_e32 v84, v208, v84
	v_exp_f32_e32 v213, v93
	v_add_f32_e32 v84, v209, v84
	v_exp_f32_e32 v214, v94
	v_add_f32_e32 v84, v210, v84
	v_exp_f32_e32 v215, v95
	v_add_f32_e32 v84, v211, v84
	v_add_f32_e32 v84, v212, v84
	v_add_f32_e32 v84, v213, v84
	v_add_f32_e32 v84, v214, v84
	v_add_f32_e32 v84, v215, v84
	v_mov_b32_e32 v85, v84
	s_nop 1
	v_permlane32_swap_b32_e32 v84, v85
	v_add_f32_e32 v84, v84, v85
	v_add_f32_e32 v146, v146, v84
	v_cvt_pk_bf16_f32 v84, v220, v221
	v_cvt_pk_bf16_f32 v85, v222, v223
	v_cvt_pk_bf16_f32 v86, v224, v225
	v_cvt_pk_bf16_f32 v87, v226, v227
	v_cvt_pk_bf16_f32 v91, v234, v235
	v_cvt_pk_bf16_f32 v92, v80, v81
	v_cvt_pk_bf16_f32 v93, v82, v83
	v_cvt_pk_bf16_f32 v94, v204, v205
	v_cvt_pk_bf16_f32 v95, v206, v207
	v_cvt_pk_bf16_f32 v80, v208, v209
	v_cvt_pk_bf16_f32 v81, v210, v211
	v_cvt_pk_bf16_f32 v82, v212, v213
	v_cvt_pk_bf16_f32 v83, v214, v215
	s_nop 0
	s_cmp_gt_i32 s18, 0
	s_cselect_b32 s20, -1, 2
	s_add_i32 s8, s8, s1
	s_add_i32 s20, s20, s18
	v_lshl_add_u64 v[204:205], v[158:159], 0, s[74:75]
	s_mov_b32 m0, s8
	v_lshl_add_u64 v[158:159], v[158:159], 0, s[76:77]
	global_load_lds_dwordx4 v[204:205], off
	s_add_i32 m0, s8, 0x2000
	s_lshl_b32 s8, s20, 14
	s_add_i32 s8, s5, s8
	global_load_lds_dwordx4 v[158:159], off
	v_lshl_add_u64 v[158:159], v[156:157], 0, s[78:79]
	s_mov_b32 m0, s8
	v_lshl_add_u64 v[156:157], v[156:157], 0, s[80:81]
	global_load_lds_dwordx4 v[158:159], off
	s_add_i32 m0, s8, 0x2000
	s_nop 0
	global_load_lds_dwordx4 v[156:157], off
	v_lshl_add_u64 v[156:157], v[160:161], 0, s[82:83]
	s_add_i32 m0, s19, s1
	s_nop 0
	global_load_lds_dwordx4 v[156:157], off
	v_lshl_add_u32 v160, s18, 14, v166
	ds_read_b64_tr_b16 v[156:157], v160 offset:0
	ds_read_b64_tr_b16 v[158:159], v160 offset:0x800
	ds_read_b64_tr_b16 v[204:205], v160 offset:0x1000
	ds_read_b64_tr_b16 v[206:207], v160 offset:0x1800
	ds_read_b64_tr_b16 v[208:209], v160 offset:0x2000
	ds_read_b64_tr_b16 v[210:211], v160 offset:0x2800
	ds_read_b64_tr_b16 v[212:213], v160 offset:0x3000
	ds_read_b64_tr_b16 v[214:215], v160 offset:0x3800
	v_exp_f32_e32 v161, v104
	s_waitcnt lgkmcnt(0)
	s_add_i32 s8, s18, 1
	v_mfma_f32_32x32x16_bf16 v[48:63], v[84:87], v[156:159], v[48:63]
	ds_read_b64_tr_b16 v[156:157], v160 offset:0x200
	ds_read_b64_tr_b16 v[158:159], v160 offset:0xa00
	s_cmp_lg_u32 s18, 2
	s_cselect_b32 s18, s8, 0
	s_add_i32 s15, s15, 2
	v_lshl_add_u64 v[150:151], v[150:151], 0, s[84:85]
	v_lshl_add_u64 v[152:153], v[152:153], 0, s[86:87]
	v_mfma_f32_32x32x16_bf16 v[48:63], v[88:91], v[204:207], v[48:63]
	ds_read_b64_tr_b16 v[204:205], v160 offset:0x1200
	ds_read_b64_tr_b16 v[206:207], v160 offset:0x1a00
	v_lshl_add_u64 v[154:155], v[154:155], 0, s[86:87]
	s_cmpk_gt_u32 s15, 0x7c
	v_mfma_f32_32x32x16_bf16 v[48:63], v[92:95], v[208:211], v[48:63]
	ds_read_b64_tr_b16 v[208:209], v160 offset:0x2200
	ds_read_b64_tr_b16 v[210:211], v160 offset:0x2a00
	ds_read_b64_tr_b16 v[216:217], v160 offset:0x3200
	ds_read_b64_tr_b16 v[218:219], v160 offset:0x3a00
	s_nop 0
	s_waitcnt lgkmcnt(0)
	s_nop 0
	v_mfma_f32_32x32x16_bf16 v[32:47], v[84:87], v[156:159], v[32:47]
	ds_read_b64_tr_b16 v[156:157], v160 offset:0x400
	ds_read_b64_tr_b16 v[158:159], v160 offset:0xc00
	v_mfma_f32_32x32x16_bf16 v[32:47], v[88:91], v[204:207], v[32:47]
	ds_read_b64_tr_b16 v[204:205], v160 offset:0x1400
	ds_read_b64_tr_b16 v[206:207], v160 offset:0x1c00
	v_mfma_f32_32x32x16_bf16 v[32:47], v[92:95], v[208:211], v[32:47]
	ds_read_b64_tr_b16 v[208:209], v160 offset:0x2400
	ds_read_b64_tr_b16 v[210:211], v160 offset:0x2c00
	v_mfma_f32_32x32x16_bf16 v[48:63], v[80:83], v[212:215], v[48:63]
	ds_read_b64_tr_b16 v[212:213], v160 offset:0x3400
	ds_read_b64_tr_b16 v[214:215], v160 offset:0x3c00
	s_nop 0
	s_waitcnt lgkmcnt(0)
	v_mfma_f32_32x32x16_bf16 v[32:47], v[80:83], v[216:219], v[32:47]
	v_mfma_f32_32x32x16_bf16 v[16:31], v[84:87], v[156:159], v[16:31]
	ds_read_b64_tr_b16 v[156:157], v160 offset:0x600
	ds_read_b64_tr_b16 v[158:159], v160 offset:0xe00
	ds_read_b64_tr_b16 v[216:217], v160 offset:0x1600
	ds_read_b64_tr_b16 v[218:219], v160 offset:0x1e00
	ds_read_b64_tr_b16 v[220:221], v160 offset:0x2600
	ds_read_b64_tr_b16 v[222:223], v160 offset:0x2e00
	ds_read_b64_tr_b16 v[224:225], v160 offset:0x3600
	ds_read_b64_tr_b16 v[226:227], v160 offset:0x3e00
	v_mfma_f32_32x32x16_bf16 v[16:31], v[88:91], v[204:207], v[16:31]
	s_waitcnt lgkmcnt(0)
	v_exp_f32_e32 v206, v102
	v_exp_f32_e32 v207, v103
	v_exp_f32_e32 v205, v105
	v_exp_f32_e32 v160, v106
	v_exp_f32_e32 v204, v107
	v_mfma_f32_32x32x16_bf16 v[0:15], v[84:87], v[156:159], v[0:15]
	v_exp_f32_e32 v157, v108
	v_exp_f32_e32 v159, v109
	v_exp_f32_e32 v156, v110
	v_exp_f32_e32 v158, v111
	v_mfma_f32_32x32x16_bf16 v[0:15], v[88:91], v[216:219], v[0:15]
	v_mfma_f32_32x32x16_bf16 v[16:31], v[92:95], v[208:211], v[16:31]
	v_exp_f32_e32 v211, v96
	v_exp_f32_e32 v209, v98
	v_exp_f32_e32 v208, v100
	v_exp_f32_e32 v210, v101
	v_mfma_f32_32x32x16_bf16 v[0:15], v[92:95], v[220:223], v[0:15]
	v_mfma_f32_32x32x16_bf16 v[16:31], v[80:83], v[212:215], v[16:31]
	v_exp_f32_e32 v213, v97
	v_exp_f32_e32 v212, v99
	v_mfma_f32_32x32x16_bf16 v[0:15], v[80:83], v[224:227], v[0:15]
	s_cbranch_scc0 .LBB0_808
	s_and_b32 s0, s0, 0x3fffffc0
	s_waitcnt vmcnt(0)
	s_lshl_b32 s0, s0, 2
	s_waitcnt lgkmcnt(0)
	s_add_i32 s5, s0, 0
	s_add_i32 s5, s5, 0x18000
	s_barrier
	ds_read_b128 v[80:83], v192
	ds_read_b128 v[84:87], v192 offset:8192
	v_exp_f32_e32 v154, v64
	v_add_f32_e32 v64, 0, v211
	v_add_f32_e32 v64, v213, v64
	s_waitcnt lgkmcnt(0)
	v_mfma_f32_32x32x16_bf16 v[96:111], v[80:83], v[140:143], 0
	v_add_f32_e32 v64, v209, v64
	v_add_f32_e32 v64, v212, v64
	v_add_f32_e32 v64, v208, v64
	v_add_f32_e32 v64, v210, v64
	v_add_f32_e32 v64, v206, v64
	v_add_f32_e32 v64, v207, v64
	v_add_f32_e32 v64, v161, v64
	v_mfma_f32_32x32x16_bf16 v[80:95], v[84:87], v[140:143], 0
	ds_read_b128 v[140:143], v193
	ds_read_b128 v[150:153], v193 offset:8192
	v_add_f32_e32 v64, v205, v64
	v_add_f32_e32 v64, v160, v64
	v_add_f32_e32 v64, v204, v64
	v_add_f32_e32 v64, v157, v64
	v_exp_f32_e32 v155, v65
	v_add_f32_e32 v64, v159, v64
	s_waitcnt lgkmcnt(0)
	v_mfma_f32_32x32x16_bf16 v[96:111], v[140:143], v[136:139], v[96:111]
	v_add_f32_e32 v64, v156, v64
	v_add_f32_e32 v64, v158, v64
	v_add_f32_e32 v64, v154, v64
	v_add_f32_e32 v64, v155, v64
	v_exp_f32_e32 v218, v75
	v_exp_f32_e32 v79, v79
	v_cvt_pk_bf16_f32 v65, v209, v212
	v_mfma_f32_32x32x16_bf16 v[80:95], v[150:153], v[136:139], v[80:95]
	ds_read_b128 v[136:139], v194
	ds_read_b128 v[140:143], v194 offset:8192
	s_waitcnt lgkmcnt(0)
	v_mfma_f32_32x32x16_bf16 v[96:111], v[136:139], v[132:135], v[96:111]
	v_mfma_f32_32x32x16_bf16 v[80:95], v[140:143], v[132:135], v[80:95]
	ds_read_b128 v[132:135], v195
	ds_read_b128 v[136:139], v195 offset:8192
	s_waitcnt lgkmcnt(0)
	v_mfma_f32_32x32x16_bf16 v[96:111], v[132:135], v[128:131], v[96:111]
	v_mfma_f32_32x32x16_bf16 v[80:95], v[136:139], v[128:131], v[80:95]
	ds_read_b128 v[128:131], v196
	ds_read_b128 v[132:135], v196 offset:8192
	s_waitcnt lgkmcnt(0)
	v_mfma_f32_32x32x16_bf16 v[96:111], v[128:131], v[124:127], v[96:111]
	ds_read_b128 v[128:131], v197
	v_mfma_f32_32x32x16_bf16 v[80:95], v[132:135], v[124:127], v[80:95]
	ds_read_b128 v[124:127], v197 offset:8192
	ds_read_b128 v[132:135], v198
	ds_read_b128 v[136:139], v198 offset:8192
	ds_read_b128 v[140:143], v199
	ds_read_b128 v[150:153], v199 offset:8192
	ds_read_b128 v[168:171], v200
	ds_read_b128 v[172:175], v200 offset:4096
	v_exp_f32_e32 v200, v67
	v_cvt_pk_bf16_f32 v67, v206, v207
	s_nop 0
	s_waitcnt lgkmcnt(0)
	v_mfma_f32_32x32x16_bf16 v[96:111], v[128:131], v[120:123], v[96:111]
	ds_read_b128 v[128:131], v167
	ds_read_b128 v[176:179], v167 offset:8192
	ds_read_b128 v[180:183], v201
	ds_read_b128 v[184:187], v201 offset:4096
	ds_read_b128 v[188:191], v202
	ds_read_b128 v[192:195], v202 offset:4096
	ds_read_b128 v[196:199], v167 offset:16384
	ds_read_b128 v[214:217], v167 offset:24576
	v_exp_f32_e32 v167, v66
	v_exp_f32_e32 v201, v68
	v_exp_f32_e32 v202, v73
	v_cvt_pk_bf16_f32 v66, v208, v210
	v_add_f32_e32 v64, v167, v64
	v_add_f32_e32 v64, v200, v64
	v_mfma_f32_32x32x16_bf16 v[80:95], v[124:127], v[120:123], v[80:95]
	v_add_f32_e32 v64, v201, v64
	ds_read_b128 v[120:123], v203
	ds_read_b128 v[124:127], v203 offset:4096
	v_exp_f32_e32 v203, v74
	v_cvt_pk_bf16_f32 v68, v161, v205
	v_cvt_pk_bf16_f32 v73, v167, v200
	v_mfma_f32_32x32x16_bf16 v[96:111], v[132:135], v[116:119], v[96:111]
	v_exp_f32_e32 v132, v69
	v_exp_f32_e32 v133, v70
	v_exp_f32_e32 v134, v71
	v_exp_f32_e32 v135, v72
	v_add_f32_e32 v64, v132, v64
	v_add_f32_e32 v64, v133, v64
	v_add_f32_e32 v64, v134, v64
	v_mfma_f32_32x32x16_bf16 v[80:95], v[136:139], v[116:119], v[80:95]
	v_exp_f32_e32 v116, v76
	v_add_f32_e32 v64, v135, v64
	v_exp_f32_e32 v117, v77
	v_add_f32_e32 v64, v202, v64
	v_exp_f32_e32 v118, v78
	v_add_f32_e32 v64, v203, v64
	v_add_f32_e32 v64, v218, v64
	v_mfma_f32_32x32x16_bf16 v[96:111], v[140:143], v[112:115], v[96:111]
	v_add_f32_e32 v64, v116, v64
	v_add_f32_e32 v64, v117, v64
	v_add_f32_e32 v64, v118, v64
	v_cvt_pk_bf16_f32 v69, v160, v204
	v_cvt_pk_bf16_f32 v70, v157, v159
	v_cvt_pk_bf16_f32 v71, v156, v158
	v_cvt_pk_bf16_f32 v72, v154, v155
	v_mfma_f32_32x32x16_bf16 v[80:95], v[150:153], v[112:115], v[80:95]
	v_add_f32_e32 v112, v79, v64
	v_mov_b32_e32 v114, v112
	s_nop 1
	v_permlane32_swap_b32_e32 v112, v114
	v_cvt_pk_bf16_f32 v64, v211, v213
	v_cvt_pk_bf16_f32 v74, v201, v132
	v_cvt_pk_bf16_f32 v75, v133, v134
	s_waitcnt lgkmcnt(0)
	v_mfma_f32_32x32x16_bf16 v[96:111], v[168:171], v[128:131], v[96:111]
	v_cvt_pk_bf16_f32 v76, v135, v202
	v_cvt_pk_bf16_f32 v77, v203, v218
	v_cvt_pk_bf16_f32 v78, v116, v117
	v_cvt_pk_bf16_f32 v79, v118, v79
	v_mfma_f32_32x32x16_bf16 v[80:95], v[172:175], v[128:131], v[80:95]
	v_mfma_f32_32x32x16_bf16 v[96:111], v[180:183], v[176:179], v[96:111]
	v_mfma_f32_32x32x16_bf16 v[80:95], v[184:187], v[176:179], v[80:95]
	v_mfma_f32_32x32x16_bf16 v[96:111], v[188:191], v[196:199], v[96:111]
	v_mfma_f32_32x32x16_bf16 v[80:95], v[192:195], v[196:199], v[80:95]
	v_mfma_f32_32x32x16_bf16 v[96:111], v[120:123], v[214:217], v[96:111]
	v_mfma_f32_32x32x16_bf16 v[80:95], v[124:127], v[214:217], v[80:95]
	ds_read_b64_tr_b16 v[116:117], v166 offset:0
	ds_read_b64_tr_b16 v[118:119], v166 offset:0x800
	ds_read_b64_tr_b16 v[120:121], v166 offset:0x1000
	ds_read_b64_tr_b16 v[122:123], v166 offset:0x1800
	ds_read_b64_tr_b16 v[124:125], v166 offset:0x2000
	ds_read_b64_tr_b16 v[126:127], v166 offset:0x2800
	ds_read_b64_tr_b16 v[128:129], v166 offset:0x3000
	ds_read_b64_tr_b16 v[130:131], v166 offset:0x3800
	s_nop 10
	v_exp_f32_e32 v96, v96
	s_waitcnt lgkmcnt(0)
	v_exp_f32_e32 v97, v97
	v_mfma_f32_32x32x16_bf16 v[48:63], v[64:67], v[116:119], v[48:63]
	ds_read_b64_tr_b16 v[116:117], v166 offset:0x200
	ds_read_b64_tr_b16 v[118:119], v166 offset:0xa00
	ds_read_b64_tr_b16 v[132:133], v166 offset:0x1200
	ds_read_b64_tr_b16 v[134:135], v166 offset:0x1a00
	ds_read_b64_tr_b16 v[136:137], v166 offset:0x2200
	ds_read_b64_tr_b16 v[138:139], v166 offset:0x2a00
	v_exp_f32_e32 v98, v98
	v_mfma_f32_32x32x16_bf16 v[48:63], v[68:71], v[120:123], v[48:63]
	ds_read_b64_tr_b16 v[120:121], v166 offset:0x3200
	ds_read_b64_tr_b16 v[122:123], v166 offset:0x3a00
	v_exp_f32_e32 v99, v99
	s_waitcnt lgkmcnt(0)
	ds_read_b64_tr_b16 v[140:141], v166 offset:0x400
	ds_read_b64_tr_b16 v[142:143], v166 offset:0xc00
	ds_read_b64_tr_b16 v[150:151], v166 offset:0x1400
	v_mfma_f32_32x32x16_bf16 v[48:63], v[72:75], v[124:127], v[48:63]
	ds_read_b64_tr_b16 v[152:153], v166 offset:0x1c00
	ds_read_b64_tr_b16 v[124:125], v166 offset:0x2400
	ds_read_b64_tr_b16 v[126:127], v166 offset:0x2c00
	ds_read_b64_tr_b16 v[154:155], v166 offset:0x3400
	ds_read_b64_tr_b16 v[156:157], v166 offset:0x3c00
	v_exp_f32_e32 v100, v100
	s_waitcnt lgkmcnt(0)
	v_add_f32_e32 v113, 0, v96
	v_mfma_f32_32x32x16_bf16 v[48:63], v[76:79], v[128:131], v[48:63]
	ds_read_b64_tr_b16 v[128:129], v166 offset:0x600
	ds_read_b64_tr_b16 v[130:131], v166 offset:0xe00
	ds_read_b64_tr_b16 v[158:159], v166 offset:0x1600
	ds_read_b64_tr_b16 v[160:161], v166 offset:0x1e00
	ds_read_b64_tr_b16 v[168:169], v166 offset:0x2600
	ds_read_b64_tr_b16 v[170:171], v166 offset:0x2e00
	ds_read_b64_tr_b16 v[172:173], v166 offset:0x3600
	ds_read_b64_tr_b16 v[174:175], v166 offset:0x3e00
	v_exp_f32_e32 v101, v101
	v_add_f32_e32 v113, v97, v113
	v_mfma_f32_32x32x16_bf16 v[32:47], v[64:67], v[116:119], v[32:47]
	s_waitcnt lgkmcnt(0)
	v_exp_f32_e32 v102, v102
	v_add_f32_e32 v113, v98, v113
	v_exp_f32_e32 v103, v103
	v_add_f32_e32 v113, v99, v113
	v_exp_f32_e32 v104, v104
	v_add_f32_e32 v113, v100, v113
	v_mfma_f32_32x32x16_bf16 v[16:31], v[64:67], v[140:143], v[16:31]
	v_exp_f32_e32 v105, v105
	v_add_f32_e32 v113, v101, v113
	v_exp_f32_e32 v106, v106
	v_add_f32_e32 v113, v102, v113
	v_exp_f32_e32 v107, v107
	v_add_f32_e32 v113, v103, v113
	v_exp_f32_e32 v108, v108
	v_mfma_f32_32x32x16_bf16 v[0:15], v[64:67], v[128:131], v[0:15]
	v_add_f32_e32 v113, v104, v113
	v_exp_f32_e32 v109, v109
	v_add_f32_e32 v113, v105, v113
	v_exp_f32_e32 v110, v110
	v_add_f32_e32 v113, v106, v113
	v_exp_f32_e32 v111, v111
	v_add_f32_e32 v113, v107, v113
	v_mfma_f32_32x32x16_bf16 v[32:47], v[68:71], v[132:135], v[32:47]
	v_exp_f32_e32 v80, v80
	v_add_f32_e32 v113, v108, v113
	v_exp_f32_e32 v81, v81
	v_add_f32_e32 v113, v109, v113
	v_exp_f32_e32 v82, v82
	v_add_f32_e32 v113, v110, v113
	v_exp_f32_e32 v83, v83
	v_mfma_f32_32x32x16_bf16 v[16:31], v[68:71], v[150:153], v[16:31]
	v_add_f32_e32 v113, v111, v113
	v_exp_f32_e32 v84, v84
	v_add_f32_e32 v113, v80, v113
	v_exp_f32_e32 v85, v85
	v_add_f32_e32 v113, v81, v113
	v_exp_f32_e32 v86, v86
	v_add_f32_e32 v113, v82, v113
	v_mfma_f32_32x32x16_bf16 v[0:15], v[68:71], v[158:161], v[0:15]
	v_exp_f32_e32 v87, v87
	v_add_f32_e32 v113, v83, v113
	v_exp_f32_e32 v88, v88
	v_add_f32_e32 v113, v84, v113
	v_exp_f32_e32 v89, v89
	v_add_f32_e32 v113, v85, v113
	v_exp_f32_e32 v90, v90
	v_mfma_f32_32x32x16_bf16 v[32:47], v[72:75], v[136:139], v[32:47]
	v_add_f32_e32 v64, v86, v113
	v_exp_f32_e32 v91, v91
	v_add_f32_e32 v64, v87, v64
	v_exp_f32_e32 v92, v92
	v_add_f32_e32 v64, v88, v64
	v_exp_f32_e32 v93, v93
	v_add_f32_e32 v64, v89, v64
	v_mfma_f32_32x32x16_bf16 v[16:31], v[72:75], v[124:127], v[16:31]
	v_exp_f32_e32 v94, v94
	v_add_f32_e32 v64, v90, v64
	v_exp_f32_e32 v95, v95
	v_add_f32_e32 v64, v91, v64
	v_add_f32_e32 v64, v92, v64
	v_add_f32_e32 v64, v93, v64
	v_add_f32_e32 v64, v94, v64
	v_mfma_f32_32x32x16_bf16 v[0:15], v[72:75], v[168:171], v[0:15]
	v_add_f32_e32 v113, v95, v64
	v_mov_b32_e32 v115, v113
	s_nop 1
	v_permlane32_swap_b32_e32 v113, v115
	v_cvt_pk_bf16_f32 v64, v96, v97
	v_cvt_pk_bf16_f32 v65, v98, v99
	v_cvt_pk_bf16_f32 v66, v100, v101
	v_mfma_f32_32x32x16_bf16 v[32:47], v[76:79], v[120:123], v[32:47]
	v_cvt_pk_bf16_f32 v67, v102, v103
	v_cvt_pk_bf16_f32 v68, v104, v105
	v_cvt_pk_bf16_f32 v69, v106, v107
	v_cvt_pk_bf16_f32 v70, v108, v109
	v_cvt_pk_bf16_f32 v71, v110, v111
	v_cvt_pk_bf16_f32 v72, v80, v81
	v_cvt_pk_bf16_f32 v73, v82, v83
	v_mfma_f32_32x32x16_bf16 v[16:31], v[76:79], v[154:157], v[16:31]
	v_cvt_pk_bf16_f32 v74, v84, v85
	v_cvt_pk_bf16_f32 v75, v86, v87
	v_mfma_f32_32x32x16_bf16 v[0:15], v[76:79], v[172:175], v[0:15]
	v_cvt_pk_bf16_f32 v76, v88, v89
	v_cvt_pk_bf16_f32 v77, v90, v91
	v_cvt_pk_bf16_f32 v78, v92, v93
	v_cvt_pk_bf16_f32 v79, v94, v95
	s_cmp_lg_u32 0, -1
	s_cselect_b32 s0, 0, 0
	s_addk_i32 s0, 0x4000
	v_add_u32_e32 v100, s0, v165
	ds_read_b64_tr_b16 v[80:81], v100 offset:0
	ds_read_b64_tr_b16 v[82:83], v100 offset:0x800
	ds_read_b64_tr_b16 v[84:85], v100 offset:0x1000
	ds_read_b64_tr_b16 v[86:87], v100 offset:0x1800
	ds_read_b64_tr_b16 v[88:89], v100 offset:0x2000
	ds_read_b64_tr_b16 v[90:91], v100 offset:0x2800
	ds_read_b64_tr_b16 v[92:93], v100 offset:0x3000
	ds_read_b64_tr_b16 v[94:95], v100 offset:0x3800
	s_nop 0
	s_waitcnt lgkmcnt(0)
	s_nop 0
	v_mfma_f32_32x32x16_bf16 v[48:63], v[64:67], v[80:83], v[48:63]
	ds_read_b64_tr_b16 v[80:81], v100 offset:0x200
	ds_read_b64_tr_b16 v[82:83], v100 offset:0xa00
	v_mfma_f32_32x32x16_bf16 v[48:63], v[68:71], v[84:87], v[48:63]
	ds_read_b64_tr_b16 v[84:85], v100 offset:0x1200
	ds_read_b64_tr_b16 v[86:87], v100 offset:0x1a00
	v_mfma_f32_32x32x16_bf16 v[48:63], v[72:75], v[88:91], v[48:63]
	ds_read_b64_tr_b16 v[88:89], v100 offset:0x2200
	ds_read_b64_tr_b16 v[90:91], v100 offset:0x2a00
	ds_read_b64_tr_b16 v[96:97], v100 offset:0x3200
	ds_read_b64_tr_b16 v[98:99], v100 offset:0x3a00
	s_nop 0
	s_waitcnt lgkmcnt(0)
	s_nop 0
	v_mfma_f32_32x32x16_bf16 v[32:47], v[64:67], v[80:83], v[32:47]
	ds_read_b64_tr_b16 v[80:81], v100 offset:0x400
	ds_read_b64_tr_b16 v[82:83], v100 offset:0xc00
	v_mfma_f32_32x32x16_bf16 v[32:47], v[68:71], v[84:87], v[32:47]
	ds_read_b64_tr_b16 v[84:85], v100 offset:0x1400
	ds_read_b64_tr_b16 v[86:87], v100 offset:0x1c00
	v_mfma_f32_32x32x16_bf16 v[48:63], v[76:79], v[92:95], v[48:63]
	v_mfma_f32_32x32x16_bf16 v[32:47], v[72:75], v[88:91], v[32:47]
	ds_read_b64_tr_b16 v[88:89], v100 offset:0x2400
	ds_read_b64_tr_b16 v[90:91], v100 offset:0x2c00
	ds_read_b64_tr_b16 v[92:93], v100 offset:0x3400
	ds_read_b64_tr_b16 v[94:95], v100 offset:0x3c00
	s_nop 0
	s_waitcnt lgkmcnt(0)
	s_nop 0
	v_mfma_f32_32x32x16_bf16 v[16:31], v[64:67], v[80:83], v[16:31]
	ds_read_b64_tr_b16 v[80:81], v100 offset:0x600
	ds_read_b64_tr_b16 v[82:83], v100 offset:0xe00
	v_mfma_f32_32x32x16_bf16 v[16:31], v[68:71], v[84:87], v[16:31]
	ds_read_b64_tr_b16 v[84:85], v100 offset:0x1600
	ds_read_b64_tr_b16 v[86:87], v100 offset:0x1e00
	v_mfma_f32_32x32x16_bf16 v[16:31], v[72:75], v[88:91], v[16:31]
	ds_read_b64_tr_b16 v[88:89], v100 offset:0x2600
	ds_read_b64_tr_b16 v[90:91], v100 offset:0x2e00
	v_mfma_f32_32x32x16_bf16 v[16:31], v[76:79], v[92:95], v[16:31]
	ds_read_b64_tr_b16 v[92:93], v100 offset:0x3600
	ds_read_b64_tr_b16 v[94:95], v100 offset:0x3e00
	s_nop 0
	s_waitcnt lgkmcnt(0)
	s_nop 0
	v_mfma_f32_32x32x16_bf16 v[0:15], v[64:67], v[80:83], v[0:15]
	v_mfma_f32_32x32x16_bf16 v[0:15], v[68:71], v[84:87], v[0:15]
	v_mfma_f32_32x32x16_bf16 v[0:15], v[72:75], v[88:91], v[0:15]
	v_mfma_f32_32x32x16_bf16 v[32:47], v[76:79], v[96:99], v[32:47]
	v_mfma_f32_32x32x16_bf16 v[0:15], v[76:79], v[92:95], v[0:15]
	s_setprio 0
	v_cmp_gt_u32_e32 vcc, 32, v149
	s_and_saveexec_b64 s[0:1], vcc
	s_cbranch_execz .LBB0_781
	v_pk_add_f32 v[64:65], v[112:113], v[114:115]
	v_lshl_add_u32 v66, v162, 2, s5
	v_add_f32_e32 v64, v146, v64
	v_add_f32_e32 v64, v64, v65
	ds_write_b32 v66, v64
	s_branch .LBB0_781
